# plan A + attention QK fragments read ahead + P0 x conversion two rows per iteration
# speedup vs baseline: 1.0061x; 1.0061x over previous
.LBB0_26:
	s_or_b64 exec, exec, s[2:3]
	v_fmamk_f32 v35, v35, 0x3a800000, v21
	v_fmamk_f32 v58, v58, 0x3a800000, v21
	v_mul_f32_e32 v36, 0x4b800000, v35
	v_mul_f32_e32 v59, 0x4b800000, v58
	v_cmp_gt_f32_e64 s[2:3], s0, v35
	v_cmp_gt_f32_e64 s[26:27], s0, v58
	v_add_u32_e32 v34, s12, v34
	v_lshl_add_u64 v[66:67], v[26:27], 0, s[22:23]
	v_cndmask_b32_e64 v35, v35, v36, s[2:3]
	v_cndmask_b32_e64 v58, v58, v59, s[26:27]
	v_rsq_f32_e32 v35, v35
	v_rsq_f32_e32 v58, v58
	v_add_u32_e32 v34, s12, v34
	v_mul_f32_e32 v36, 0x45800000, v35
	v_mul_f32_e32 v59, 0x45800000, v58
	v_cndmask_b32_e64 v36, v35, v36, s[2:3]
	v_cndmask_b32_e64 v60, v58, v59, s[26:27]
	v_pk_mul_f32 v[2:3], v[2:3], v[36:37] op_sel_hi:[1,0]
	v_pk_mul_f32 v[4:5], v[4:5], v[36:37] op_sel_hi:[1,0]
	v_cvt_pk_bf16_f32 v2, v2, v3
	v_cvt_pk_bf16_f32 v3, v4, v5
	global_store_dwordx2 v[26:27], v[2:3], off offset:-512
	v_pk_mul_f32 v[2:3], v[6:7], v[36:37] op_sel_hi:[1,0]
	v_pk_mul_f32 v[4:5], v[8:9], v[36:37] op_sel_hi:[1,0]
	v_cvt_pk_bf16_f32 v2, v2, v3
	v_cvt_pk_bf16_f32 v3, v4, v5
	v_pk_mul_f32 v[14:15], v[14:15], v[36:37] op_sel_hi:[1,0]
	v_pk_mul_f32 v[16:17], v[16:17], v[36:37] op_sel_hi:[1,0]
	global_store_dwordx2 v[26:27], v[2:3], off
	v_pk_mul_f32 v[2:3], v[10:11], v[36:37] op_sel_hi:[1,0]
	v_pk_mul_f32 v[4:5], v[12:13], v[36:37] op_sel_hi:[1,0]
	v_cvt_pk_bf16_f32 v14, v14, v15
	v_cvt_pk_bf16_f32 v15, v16, v17
	v_cvt_pk_bf16_f32 v2, v2, v3
	v_cvt_pk_bf16_f32 v3, v4, v5
	global_store_dwordx2 v[26:27], v[14:15], off offset:-1024
	global_store_dwordx2 v[26:27], v[2:3], off offset:512
	v_pk_mul_f32 v[42:43], v[42:43], v[60:61] op_sel_hi:[1,0]
	v_pk_mul_f32 v[44:45], v[44:45], v[60:61] op_sel_hi:[1,0]
	v_cvt_pk_bf16_f32 v42, v42, v43
	v_cvt_pk_bf16_f32 v43, v44, v45
	global_store_dwordx2 v[66:67], v[42:43], off offset:-512
	v_pk_mul_f32 v[46:47], v[46:47], v[60:61] op_sel_hi:[1,0]
	v_pk_mul_f32 v[48:49], v[48:49], v[60:61] op_sel_hi:[1,0]
	v_cvt_pk_bf16_f32 v46, v46, v47
	v_cvt_pk_bf16_f32 v47, v48, v49
	v_pk_mul_f32 v[54:55], v[54:55], v[60:61] op_sel_hi:[1,0]
	v_pk_mul_f32 v[56:57], v[56:57], v[60:61] op_sel_hi:[1,0]
	global_store_dwordx2 v[66:67], v[46:47], off
	v_pk_mul_f32 v[50:51], v[50:51], v[60:61] op_sel_hi:[1,0]
	v_pk_mul_f32 v[52:53], v[52:53], v[60:61] op_sel_hi:[1,0]
	v_cvt_pk_bf16_f32 v54, v54, v55
	v_cvt_pk_bf16_f32 v55, v56, v57
	v_cvt_pk_bf16_f32 v50, v50, v51
	v_cvt_pk_bf16_f32 v51, v52, v53
	v_cmp_lt_i32_e64 s[2:3], s1, v34
	global_store_dwordx2 v[66:67], v[54:55], off offset:-1024
	global_store_dwordx2 v[66:67], v[50:51], off offset:512
	v_lshl_add_u64 v[22:23], v[22:23], 0, s[14:15]
	v_lshl_add_u64 v[24:25], v[24:25], 0, s[20:21]
	v_lshl_add_u64 v[26:27], v[66:67], 0, s[22:23]
	v_lshl_add_u64 v[22:23], v[22:23], 0, s[14:15]
	v_lshl_add_u64 v[24:25], v[24:25], 0, s[20:21]
	s_or_b64 s[24:25], s[2:3], s[24:25]
	s_andn2_b64 exec, exec, s[24:25]
	s_cbranch_execz .LBB0_29
.LBB0_27:
	v_lshl_add_u64 v[62:63], v[24:25], 0, s[20:21]
	global_load_dwordx4 v[14:17], v[24:25], off offset:-2048
	global_load_dwordx4 v[2:5], v[24:25], off offset:-1024
	global_load_dwordx4 v[6:9], v[24:25], off
	global_load_dwordx4 v[10:13], v[24:25], off offset:1024
	global_load_dwordx4 v[54:57], v[62:63], off offset:-2048
	global_load_dwordx4 v[42:45], v[62:63], off offset:-1024
	global_load_dwordx4 v[46:49], v[62:63], off
	global_load_dwordx4 v[50:53], v[62:63], off offset:1024
	s_waitcnt vmcnt(7)
	v_mul_f32_e32 v35, v15, v15
	s_waitcnt vmcnt(6)
	v_mul_f32_e32 v36, v3, v3
	s_waitcnt vmcnt(5)
	v_mul_f32_e32 v37, v7, v7
	v_fmac_f32_e32 v35, v14, v14
	v_fmac_f32_e32 v36, v2, v2
	s_waitcnt vmcnt(4)
	v_mul_f32_e32 v38, v11, v11
	v_fmac_f32_e32 v37, v6, v6
	v_fmac_f32_e32 v35, v16, v16
	v_fmac_f32_e32 v36, v4, v4
	v_fmac_f32_e32 v38, v10, v10
	v_fmac_f32_e32 v37, v8, v8
	v_fmac_f32_e32 v35, v17, v17
	v_fmac_f32_e32 v36, v5, v5
	v_fmac_f32_e32 v38, v12, v12
	v_fmac_f32_e32 v37, v9, v9
	v_add_f32_e32 v35, v35, v36
	v_add_f32_e32 v35, v35, v37
	v_fmac_f32_e32 v38, v13, v13
	v_add_f32_e32 v35, v35, v38
	s_waitcnt vmcnt(3)
	v_mul_f32_e32 v58, v55, v55
	s_waitcnt vmcnt(2)
	v_mul_f32_e32 v59, v43, v43
	s_waitcnt vmcnt(1)
	v_mul_f32_e32 v60, v47, v47
	v_fmac_f32_e32 v58, v54, v54
	v_fmac_f32_e32 v59, v42, v42
	s_waitcnt vmcnt(0)
	v_mul_f32_e32 v61, v51, v51
	v_fmac_f32_e32 v60, v46, v46
	v_fmac_f32_e32 v58, v56, v56
	v_fmac_f32_e32 v59, v44, v44
	v_fmac_f32_e32 v61, v50, v50
	v_fmac_f32_e32 v60, v48, v48
	v_fmac_f32_e32 v58, v57, v57
	v_fmac_f32_e32 v59, v45, v45
	v_fmac_f32_e32 v61, v52, v52
	v_fmac_f32_e32 v60, v49, v49
	v_add_f32_e32 v58, v58, v59
	v_add_f32_e32 v58, v58, v60
	v_fmac_f32_e32 v61, v53, v53
	v_add_f32_e32 v58, v58, v61
	ds_bpermute_b32 v36, v1, v35
	ds_bpermute_b32 v59, v1, v58
	s_waitcnt lgkmcnt(1)
	v_add_f32_e32 v35, v35, v36
	s_waitcnt lgkmcnt(0)
	v_add_f32_e32 v58, v58, v59
	ds_bpermute_b32 v36, v19, v35
	ds_bpermute_b32 v59, v19, v58
	s_waitcnt lgkmcnt(1)
	v_add_f32_e32 v35, v35, v36
	s_waitcnt lgkmcnt(0)
	v_add_f32_e32 v58, v58, v59
	ds_bpermute_b32 v36, v30, v35
	ds_bpermute_b32 v59, v30, v58
	s_waitcnt lgkmcnt(1)
	v_add_f32_e32 v35, v35, v36
	s_waitcnt lgkmcnt(0)
	v_add_f32_e32 v58, v58, v59
	ds_bpermute_b32 v36, v31, v35
	ds_bpermute_b32 v59, v31, v58
	s_waitcnt lgkmcnt(1)
	v_add_f32_e32 v35, v35, v36
	s_waitcnt lgkmcnt(0)
	v_add_f32_e32 v58, v58, v59
	ds_bpermute_b32 v36, v32, v35
	ds_bpermute_b32 v59, v32, v58
	s_waitcnt lgkmcnt(1)
	v_add_f32_e32 v35, v35, v36
	s_waitcnt lgkmcnt(0)
	v_add_f32_e32 v58, v58, v59
	ds_bpermute_b32 v36, v33, v35
	ds_bpermute_b32 v59, v33, v58
	s_waitcnt lgkmcnt(1)
	v_add_f32_e32 v35, v35, v36
	s_waitcnt lgkmcnt(0)
	v_add_f32_e32 v58, v58, v59
	s_and_saveexec_b64 s[2:3], vcc
	s_cbranch_execz .LBB0_26
	v_lshl_add_u64 v[64:65], v[22:23], 0, s[14:15]
	global_store_dword v[22:23], v35, off
	global_store_dword v[64:65], v58, off
	s_branch .LBB0_26
